# P1 Z stores write-through (sc1) on v37, second measurement
# speedup vs baseline: 1.0148x; 1.0148x over previous
.LBB0_185:
	v_lshl_or_b32 v148, s65, 8, v172
	v_ashrrev_i32_e32 v149, 31, v148
	v_mov_b64_e32 v[162:163], s[36:37]
	v_mad_i64_i32 v[176:177], s[44:45], v142, s75, v[162:163]
	v_lshlrev_b64 v[164:165], 1, v[148:149]
	v_lshl_add_u64 v[148:149], v[176:177], 0, v[164:165]
	s_waitcnt lgkmcnt(0)
	v_pk_mul_f32 v[128:129], v[128:129], v[168:169] op_sel_hi:[1,0]
	v_pk_mul_f32 v[126:127], v[126:127], v[168:169] op_sel_hi:[1,0]
	v_pk_mul_f32 v[176:177], v[124:125], v[168:169] op_sel_hi:[1,0]
	v_pk_mul_f32 v[124:125], v[122:123], v[168:169] op_sel_hi:[1,0]
	v_cvt_pk_bf16_f32 v122, v126, v127
	v_cvt_pk_bf16_f32 v123, v128, v129
	v_cvt_pk_bf16_f32 v124, v124, v125
	v_cvt_pk_bf16_f32 v125, v176, v177
	global_store_dwordx4 v[148:149], v[122:125], off sc1
	v_pk_mul_f32 v[120:121], v[120:121], v[168:169] op_sel_hi:[1,0]
	v_pk_mul_f32 v[118:119], v[118:119], v[168:169] op_sel_hi:[1,0]
	v_pk_mul_f32 v[122:123], v[116:117], v[168:169] op_sel_hi:[1,0]
	v_pk_mul_f32 v[116:117], v[114:115], v[168:169] op_sel_hi:[1,0]
	v_cvt_pk_bf16_f32 v114, v118, v119
	v_cvt_pk_bf16_f32 v115, v120, v121
	v_cvt_pk_bf16_f32 v116, v116, v117
	v_cvt_pk_bf16_f32 v117, v122, v123
	global_store_dwordx4 v[148:149], v[114:117], off offset:256 sc1
	v_pk_mul_f32 v[96:97], v[96:97], v[166:167] op_sel_hi:[1,0]
	v_pk_mul_f32 v[94:95], v[94:95], v[166:167] op_sel_hi:[1,0]
	v_or_b32_e32 v114, 16, v142
	v_mov_b32_e32 v116, v169
	v_mad_i64_i32 v[114:115], s[44:45], v114, s75, v[162:163]
	v_pk_mul_f32 v[112:113], v[112:113], v[116:117] op_sel_hi:[1,0]
	v_pk_mul_f32 v[110:111], v[110:111], v[116:117] op_sel_hi:[1,0]
	v_pk_mul_f32 v[118:119], v[108:109], v[116:117] op_sel_hi:[1,0]
	v_pk_mul_f32 v[108:109], v[106:107], v[116:117] op_sel_hi:[1,0]
	v_lshl_add_u64 v[114:115], v[114:115], 0, v[164:165]
	v_cvt_pk_bf16_f32 v106, v110, v111
	v_cvt_pk_bf16_f32 v107, v112, v113
	v_cvt_pk_bf16_f32 v108, v108, v109
	v_cvt_pk_bf16_f32 v109, v118, v119
	global_store_dwordx4 v[114:115], v[106:109], off sc1
	v_pk_mul_f32 v[104:105], v[104:105], v[116:117] op_sel_hi:[1,0]
	v_pk_mul_f32 v[102:103], v[102:103], v[116:117] op_sel_hi:[1,0]
	v_pk_mul_f32 v[106:107], v[100:101], v[116:117] op_sel_hi:[1,0]
	v_pk_mul_f32 v[100:101], v[98:99], v[116:117] op_sel_hi:[1,0]
	v_cvt_pk_bf16_f32 v98, v102, v103
	v_cvt_pk_bf16_f32 v99, v104, v105
	v_cvt_pk_bf16_f32 v100, v100, v101
	v_cvt_pk_bf16_f32 v101, v106, v107
	global_store_dwordx4 v[114:115], v[98:101], off offset:256 sc1
	v_pk_mul_f32 v[88:89], v[88:89], v[166:167] op_sel_hi:[1,0]
	v_pk_mul_f32 v[86:87], v[86:87], v[166:167] op_sel_hi:[1,0]
	v_or_b32_e32 v98, 32, v142
	v_mad_i64_i32 v[98:99], s[44:45], v98, s75, v[162:163]
	v_pk_mul_f32 v[100:101], v[92:93], v[166:167] op_sel_hi:[1,0]
	v_pk_mul_f32 v[92:93], v[90:91], v[166:167] op_sel_hi:[1,0]
	v_lshl_add_u64 v[98:99], v[98:99], 0, v[164:165]
	v_cvt_pk_bf16_f32 v90, v94, v95
	v_cvt_pk_bf16_f32 v91, v96, v97
	v_cvt_pk_bf16_f32 v92, v92, v93
	v_cvt_pk_bf16_f32 v93, v100, v101
	global_store_dwordx4 v[98:99], v[90:93], off sc1
	v_pk_mul_f32 v[64:65], v[64:65], v[144:145] op_sel_hi:[1,0]
	v_pk_mul_f32 v[62:63], v[62:63], v[144:145] op_sel_hi:[1,0]
	v_pk_mul_f32 v[90:91], v[84:85], v[166:167] op_sel_hi:[1,0]
	v_pk_mul_f32 v[84:85], v[82:83], v[166:167] op_sel_hi:[1,0]
	v_cvt_pk_bf16_f32 v82, v86, v87
	v_cvt_pk_bf16_f32 v83, v88, v89
	v_cvt_pk_bf16_f32 v84, v84, v85
	v_cvt_pk_bf16_f32 v85, v90, v91
	global_store_dwordx4 v[98:99], v[82:85], off offset:256 sc1
	v_pk_mul_f32 v[56:57], v[56:57], v[144:145] op_sel_hi:[1,0]
	v_pk_mul_f32 v[54:55], v[54:55], v[144:145] op_sel_hi:[1,0]
	v_or_b32_e32 v82, 48, v142
	v_mov_b32_e32 v84, v167
	v_mad_i64_i32 v[82:83], s[44:45], v82, s75, v[162:163]
	v_pk_mul_f32 v[80:81], v[80:81], v[84:85] op_sel_hi:[1,0]
	v_pk_mul_f32 v[78:79], v[78:79], v[84:85] op_sel_hi:[1,0]
	v_pk_mul_f32 v[86:87], v[76:77], v[84:85] op_sel_hi:[1,0]
	v_pk_mul_f32 v[76:77], v[74:75], v[84:85] op_sel_hi:[1,0]
	v_lshl_add_u64 v[82:83], v[82:83], 0, v[164:165]
	v_cvt_pk_bf16_f32 v74, v78, v79
	v_cvt_pk_bf16_f32 v75, v80, v81
	v_cvt_pk_bf16_f32 v76, v76, v77
	v_cvt_pk_bf16_f32 v77, v86, v87
	global_store_dwordx4 v[82:83], v[74:77], off sc1
	v_pk_mul_f32 v[72:73], v[72:73], v[84:85] op_sel_hi:[1,0]
	v_pk_mul_f32 v[70:71], v[70:71], v[84:85] op_sel_hi:[1,0]
	v_pk_mul_f32 v[74:75], v[68:69], v[84:85] op_sel_hi:[1,0]
	v_pk_mul_f32 v[68:69], v[66:67], v[84:85] op_sel_hi:[1,0]
	v_cvt_pk_bf16_f32 v66, v70, v71
	v_cvt_pk_bf16_f32 v67, v72, v73
	v_cvt_pk_bf16_f32 v68, v68, v69
	v_cvt_pk_bf16_f32 v69, v74, v75
	global_store_dwordx4 v[82:83], v[66:69], off offset:256 sc1
	v_pk_mul_f32 v[32:33], v[32:33], v[140:141] op_sel_hi:[1,0]
	v_pk_mul_f32 v[30:31], v[30:31], v[140:141] op_sel_hi:[1,0]
	v_add_u32_e32 v66, 0x80, v142
	v_mad_i64_i32 v[66:67], s[44:45], v66, s75, v[162:163]
	v_pk_mul_f32 v[68:69], v[60:61], v[144:145] op_sel_hi:[1,0]
	v_pk_mul_f32 v[60:61], v[58:59], v[144:145] op_sel_hi:[1,0]
	v_lshl_add_u64 v[66:67], v[66:67], 0, v[164:165]
	v_cvt_pk_bf16_f32 v58, v62, v63
	v_cvt_pk_bf16_f32 v59, v64, v65
	v_cvt_pk_bf16_f32 v60, v60, v61
	v_cvt_pk_bf16_f32 v61, v68, v69
	global_store_dwordx4 v[66:67], v[58:61], off sc1
	v_pk_mul_f32 v[24:25], v[24:25], v[140:141] op_sel_hi:[1,0]
	v_pk_mul_f32 v[22:23], v[22:23], v[140:141] op_sel_hi:[1,0]
	v_pk_mul_f32 v[58:59], v[52:53], v[144:145] op_sel_hi:[1,0]
	v_pk_mul_f32 v[52:53], v[50:51], v[144:145] op_sel_hi:[1,0]
	v_cvt_pk_bf16_f32 v50, v54, v55
	v_cvt_pk_bf16_f32 v51, v56, v57
	v_cvt_pk_bf16_f32 v52, v52, v53
	v_cvt_pk_bf16_f32 v53, v58, v59
	global_store_dwordx4 v[66:67], v[50:53], off offset:256 sc1
	s_nop 1
	v_add_u32_e32 v50, 0x90, v142
	v_mov_b32_e32 v52, v145
	v_mad_i64_i32 v[50:51], s[44:45], v50, s75, v[162:163]
	v_pk_mul_f32 v[48:49], v[48:49], v[52:53] op_sel_hi:[1,0]
	v_pk_mul_f32 v[46:47], v[46:47], v[52:53] op_sel_hi:[1,0]
	v_pk_mul_f32 v[54:55], v[44:45], v[52:53] op_sel_hi:[1,0]
	v_pk_mul_f32 v[44:45], v[42:43], v[52:53] op_sel_hi:[1,0]
	v_lshl_add_u64 v[50:51], v[50:51], 0, v[164:165]
	v_cvt_pk_bf16_f32 v42, v46, v47
	v_cvt_pk_bf16_f32 v43, v48, v49
	v_cvt_pk_bf16_f32 v44, v44, v45
	v_cvt_pk_bf16_f32 v45, v54, v55
	global_store_dwordx4 v[50:51], v[42:45], off sc1
	v_pk_mul_f32 v[40:41], v[40:41], v[52:53] op_sel_hi:[1,0]
	v_pk_mul_f32 v[38:39], v[38:39], v[52:53] op_sel_hi:[1,0]
	v_pk_mul_f32 v[42:43], v[36:37], v[52:53] op_sel_hi:[1,0]
	v_pk_mul_f32 v[36:37], v[34:35], v[52:53] op_sel_hi:[1,0]
	v_cvt_pk_bf16_f32 v34, v38, v39
	v_cvt_pk_bf16_f32 v35, v40, v41
	v_cvt_pk_bf16_f32 v36, v36, v37
	v_cvt_pk_bf16_f32 v37, v42, v43
	global_store_dwordx4 v[50:51], v[34:37], off offset:256 sc1
	s_nop 1
	v_add_u32_e32 v34, 0xa0, v142
	v_mad_i64_i32 v[34:35], s[44:45], v34, s75, v[162:163]
	v_pk_mul_f32 v[36:37], v[28:29], v[140:141] op_sel_hi:[1,0]
	v_pk_mul_f32 v[28:29], v[26:27], v[140:141] op_sel_hi:[1,0]
	v_lshl_add_u64 v[34:35], v[34:35], 0, v[164:165]
	v_cvt_pk_bf16_f32 v26, v30, v31
	v_cvt_pk_bf16_f32 v27, v32, v33
	v_cvt_pk_bf16_f32 v28, v28, v29
	v_cvt_pk_bf16_f32 v29, v36, v37
	global_store_dwordx4 v[34:35], v[26:29], off sc1
	s_nop 1
	v_pk_mul_f32 v[26:27], v[20:21], v[140:141] op_sel_hi:[1,0]
	v_pk_mul_f32 v[20:21], v[18:19], v[140:141] op_sel_hi:[1,0]
	v_cvt_pk_bf16_f32 v18, v22, v23
	v_cvt_pk_bf16_f32 v19, v24, v25
	v_cvt_pk_bf16_f32 v20, v20, v21
	v_cvt_pk_bf16_f32 v21, v26, v27
	global_store_dwordx4 v[34:35], v[18:21], off offset:256 sc1
	s_nop 1
	v_add_u32_e32 v18, 0xb0, v142
	v_mov_b32_e32 v20, v141
	v_mad_i64_i32 v[18:19], s[44:45], v18, s75, v[162:163]
	v_pk_mul_f32 v[16:17], v[16:17], v[20:21] op_sel_hi:[1,0]
	v_pk_mul_f32 v[14:15], v[14:15], v[20:21] op_sel_hi:[1,0]
	v_pk_mul_f32 v[22:23], v[12:13], v[20:21] op_sel_hi:[1,0]
	v_pk_mul_f32 v[12:13], v[10:11], v[20:21] op_sel_hi:[1,0]
	v_lshl_add_u64 v[18:19], v[18:19], 0, v[164:165]
	v_cvt_pk_bf16_f32 v10, v14, v15
	v_cvt_pk_bf16_f32 v11, v16, v17
	v_cvt_pk_bf16_f32 v12, v12, v13
	v_cvt_pk_bf16_f32 v13, v22, v23
	global_store_dwordx4 v[18:19], v[10:13], off sc1
	v_pk_mul_f32 v[8:9], v[8:9], v[20:21] op_sel_hi:[1,0]
	v_pk_mul_f32 v[6:7], v[6:7], v[20:21] op_sel_hi:[1,0]
	v_pk_mul_f32 v[10:11], v[4:5], v[20:21] op_sel_hi:[1,0]
	v_pk_mul_f32 v[4:5], v[2:3], v[20:21] op_sel_hi:[1,0]
	v_cvt_pk_bf16_f32 v2, v6, v7
	v_cvt_pk_bf16_f32 v3, v8, v9
	v_cvt_pk_bf16_f32 v4, v4, v5
	v_cvt_pk_bf16_f32 v5, v10, v11
	global_store_dwordx4 v[18:19], v[2:5], off offset:256 sc1
	s_andn2_b64 vcc, exec, s[4:5]
	s_mov_b64 s[4:5], -1
	s_cbranch_vccnz .LBB0_167
